# P8 SwiGLU epilogue: raised priority for one wave of each SIMD pair
# speedup vs baseline: 1.0093x; 1.0042x over previous
.LBB0_2461:
	s_add_u32 s24, s22, 0xfff80080
	s_addc_u32 s25, s23, -1
	s_add_i32 s55, 0, 0x10000
	s_cmp_eq_u32 s54, 28
	s_cselect_b32 s27, s15, s25
	s_cselect_b32 s26, s35, s24
	v_add_u32_e32 v146, s55, v149
	s_cselect_b32 s25, s13, s53
	s_cselect_b32 s24, s51, s52
	s_add_i32 s58, 0, 0x14000
	ds_read_b128 v[142:145], v146
	ds_read_b128 v[154:157], v146 offset:1024
	ds_read_b128 v[158:161], v146 offset:2048
	ds_read_b128 v[162:165], v146 offset:3072
	v_add_u32_e32 v146, s58, v149
	ds_read_b128 v[166:169], v146
	ds_read_b128 v[170:173], v146 offset:1024
	ds_read_b128 v[174:177], v146 offset:2048
	ds_read_b128 v[178:181], v146 offset:3072
	v_lshl_add_u64 v[146:147], s[22:23], 0, v[138:139]
	s_add_i32 m0, s43, 0xc000
	ds_read_b128 v[182:185], v152
	ds_read_b128 v[186:189], v152 offset:1024
	ds_read_b128 v[190:193], v152 offset:2048
	ds_read_b128 v[194:197], v152 offset:3072
	ds_read_b128 v[202:205], v152 offset:4096
	ds_read_b128 v[206:209], v152 offset:5120
	ds_read_b128 v[210:213], v152 offset:6144
	ds_read_b128 v[214:217], v152 offset:7168
	global_load_lds_dwordx4 v[146:147], off
	v_lshl_add_u64 v[146:147], s[22:23], 0, v[140:141]
	s_add_i32 m0, s43, 0xe000
	s_nop 0
	global_load_lds_dwordx4 v[146:147], off
	s_waitcnt vmcnt(8)
	s_waitcnt lgkmcnt(0)
	s_barrier
	s_setprio 1
	s_waitcnt lgkmcnt(0)
	v_mfma_f32_16x16x32_bf16 v[128:131], v[142:145], v[182:185], v[128:131]
	v_mfma_f32_16x16x32_bf16 v[120:123], v[158:161], v[182:185], v[120:123]
	v_mfma_f32_16x16x32_bf16 v[112:115], v[142:145], v[190:193], v[112:115]
	v_mfma_f32_16x16x32_bf16 v[104:107], v[158:161], v[190:193], v[104:107]
	v_mfma_f32_16x16x32_bf16 v[94:97], v[142:145], v[202:205], v[94:97]
	v_mfma_f32_16x16x32_bf16 v[86:89], v[158:161], v[202:205], v[86:89]
	v_mfma_f32_16x16x32_bf16 v[78:81], v[142:145], v[210:213], v[78:81]
	v_mfma_f32_16x16x32_bf16 v[70:73], v[158:161], v[210:213], v[70:73]
	v_mfma_f32_16x16x32_bf16 v[128:131], v[154:157], v[186:189], v[128:131]
	v_mfma_f32_16x16x32_bf16 v[120:123], v[162:165], v[186:189], v[120:123]
	v_mfma_f32_16x16x32_bf16 v[112:115], v[154:157], v[194:197], v[112:115]
	v_mfma_f32_16x16x32_bf16 v[104:107], v[162:165], v[194:197], v[104:107]
	v_mfma_f32_16x16x32_bf16 v[94:97], v[154:157], v[206:209], v[94:97]
	v_mfma_f32_16x16x32_bf16 v[86:89], v[162:165], v[206:209], v[86:89]
	v_mfma_f32_16x16x32_bf16 v[78:81], v[154:157], v[214:217], v[78:81]
	v_mfma_f32_16x16x32_bf16 v[70:73], v[162:165], v[214:217], v[70:73]
	s_setprio 0
	s_setprio 1
	v_mfma_f32_16x16x32_bf16 v[124:127], v[166:169], v[182:185], v[124:127]
	v_mfma_f32_16x16x32_bf16 v[116:119], v[174:177], v[182:185], v[116:119]
	v_mfma_f32_16x16x32_bf16 v[108:111], v[166:169], v[190:193], v[108:111]
	v_mfma_f32_16x16x32_bf16 v[100:103], v[174:177], v[190:193], v[100:103]
	v_mfma_f32_16x16x32_bf16 v[90:93], v[166:169], v[202:205], v[90:93]
	v_mfma_f32_16x16x32_bf16 v[82:85], v[174:177], v[202:205], v[82:85]
	v_mfma_f32_16x16x32_bf16 v[74:77], v[166:169], v[210:213], v[74:77]
	v_mfma_f32_16x16x32_bf16 v[66:69], v[174:177], v[210:213], v[66:69]
	v_mfma_f32_16x16x32_bf16 v[124:127], v[170:173], v[186:189], v[124:127]
	v_mfma_f32_16x16x32_bf16 v[116:119], v[178:181], v[186:189], v[116:119]
	v_mfma_f32_16x16x32_bf16 v[108:111], v[170:173], v[194:197], v[108:111]
	v_mfma_f32_16x16x32_bf16 v[100:103], v[178:181], v[194:197], v[100:103]
	v_mfma_f32_16x16x32_bf16 v[90:93], v[170:173], v[206:209], v[90:93]
	v_mfma_f32_16x16x32_bf16 v[82:85], v[178:181], v[206:209], v[82:85]
	v_mfma_f32_16x16x32_bf16 v[74:77], v[170:173], v[214:217], v[74:77]
	v_mfma_f32_16x16x32_bf16 v[66:69], v[178:181], v[214:217], v[66:69]
	s_setprio 0
	s_barrier
	s_add_i32 s55, s55, s9
	v_lshl_add_u64 v[146:147], s[24:25], 0, v[98:99]
	s_mov_b32 m0, s55
	ds_read_b128 v[182:185], v152 offset:16384
	ds_read_b128 v[186:189], v152 offset:17408
	ds_read_b128 v[190:193], v152 offset:18432
	ds_read_b128 v[194:197], v152 offset:19456
	ds_read_b128 v[202:205], v152 offset:20480
	ds_read_b128 v[206:209], v152 offset:21504
	ds_read_b128 v[210:213], v152 offset:22528
	ds_read_b128 v[214:217], v152 offset:23552
	global_load_lds_dwordx4 v[146:147], off
	s_add_i32 m0, s55, 0x2000
	s_add_u32 s56, s24, 0x80000
	v_lshl_add_u64 v[198:199], s[24:25], 0, v[132:133]
	s_addc_u32 s57, s25, 0
	s_add_i32 s55, s58, s9
	global_load_lds_dwordx4 v[198:199], off
	v_lshl_add_u64 v[218:219], s[56:57], 0, v[98:99]
	s_mov_b32 m0, s55
	v_lshl_add_u64 v[220:221], s[26:27], 0, v[134:135]
	global_load_lds_dwordx4 v[218:219], off
	v_lshl_add_u64 v[218:219], s[56:57], 0, v[132:133]
	s_add_i32 m0, s55, 0x2000
	s_nop 0
	global_load_lds_dwordx4 v[218:219], off
	v_lshl_add_u64 v[218:219], s[26:27], 0, v[136:137]
	s_mov_b32 m0, s43
	s_nop 0
	global_load_lds_dwordx4 v[218:219], off
	s_mov_b32 m0, s44
	s_nop 0
	global_load_lds_dwordx4 v[220:221], off
	s_waitcnt vmcnt(8)
	s_waitcnt lgkmcnt(0)
	s_barrier
	s_setprio 1
	s_waitcnt lgkmcnt(0)
	v_mfma_f32_16x16x32_bf16 v[62:65], v[142:145], v[182:185], v[62:65]
	v_mfma_f32_16x16x32_bf16 v[54:57], v[158:161], v[182:185], v[54:57]
	v_mfma_f32_16x16x32_bf16 v[46:49], v[142:145], v[190:193], v[46:49]
	v_mfma_f32_16x16x32_bf16 v[38:41], v[158:161], v[190:193], v[38:41]
	v_mfma_f32_16x16x32_bf16 v[30:33], v[142:145], v[202:205], v[30:33]
	v_mfma_f32_16x16x32_bf16 v[22:25], v[158:161], v[202:205], v[22:25]
	v_mfma_f32_16x16x32_bf16 v[14:17], v[142:145], v[210:213], v[14:17]
	v_mfma_f32_16x16x32_bf16 v[6:9], v[158:161], v[210:213], v[6:9]
	v_mfma_f32_16x16x32_bf16 v[62:65], v[154:157], v[186:189], v[62:65]
	v_mfma_f32_16x16x32_bf16 v[54:57], v[162:165], v[186:189], v[54:57]
	v_mfma_f32_16x16x32_bf16 v[46:49], v[154:157], v[194:197], v[46:49]
	v_mfma_f32_16x16x32_bf16 v[38:41], v[162:165], v[194:197], v[38:41]
	v_mfma_f32_16x16x32_bf16 v[30:33], v[154:157], v[206:209], v[30:33]
	v_mfma_f32_16x16x32_bf16 v[22:25], v[162:165], v[206:209], v[22:25]
	v_mfma_f32_16x16x32_bf16 v[14:17], v[154:157], v[214:217], v[14:17]
	v_mfma_f32_16x16x32_bf16 v[6:9], v[162:165], v[214:217], v[6:9]
	s_setprio 0
	s_setprio 1
	v_mfma_f32_16x16x32_bf16 v[58:61], v[166:169], v[182:185], v[58:61]
	v_mfma_f32_16x16x32_bf16 v[50:53], v[174:177], v[182:185], v[50:53]
	v_mfma_f32_16x16x32_bf16 v[42:45], v[166:169], v[190:193], v[42:45]
	v_mfma_f32_16x16x32_bf16 v[34:37], v[174:177], v[190:193], v[34:37]
	v_mfma_f32_16x16x32_bf16 v[26:29], v[166:169], v[202:205], v[26:29]
	v_mfma_f32_16x16x32_bf16 v[18:21], v[174:177], v[202:205], v[18:21]
	v_mfma_f32_16x16x32_bf16 v[10:13], v[166:169], v[210:213], v[10:13]
	v_mfma_f32_16x16x32_bf16 v[2:5], v[174:177], v[210:213], v[2:5]
	v_mfma_f32_16x16x32_bf16 v[58:61], v[170:173], v[186:189], v[58:61]
	v_mfma_f32_16x16x32_bf16 v[50:53], v[178:181], v[186:189], v[50:53]
	v_mfma_f32_16x16x32_bf16 v[42:45], v[170:173], v[194:197], v[42:45]
	v_mfma_f32_16x16x32_bf16 v[34:37], v[178:181], v[194:197], v[34:37]
	v_mfma_f32_16x16x32_bf16 v[26:29], v[170:173], v[206:209], v[26:29]
	v_mfma_f32_16x16x32_bf16 v[18:21], v[178:181], v[206:209], v[18:21]
	v_mfma_f32_16x16x32_bf16 v[10:13], v[170:173], v[214:217], v[10:13]
	v_mfma_f32_16x16x32_bf16 v[2:5], v[178:181], v[214:217], v[2:5]
	s_setprio 0
	s_barrier
	s_add_i32 s55, 0, 0x18000
	v_add_u32_e32 v153, s55, v149
	s_add_i32 s56, 0, 0x1c000
	ds_read_b128 v[142:145], v153
	ds_read_b128 v[154:157], v153 offset:1024
	ds_read_b128 v[158:161], v153 offset:2048
	ds_read_b128 v[162:165], v153 offset:3072
	v_add_u32_e32 v153, s56, v149
	ds_read_b128 v[166:169], v153
	ds_read_b128 v[170:173], v153 offset:1024
	ds_read_b128 v[174:177], v153 offset:2048
	ds_read_b128 v[178:181], v153 offset:3072
	s_add_u32 s26, s26, 0x80000
	s_addc_u32 s27, s27, 0
	s_mov_b32 m0, s45
	v_lshl_add_u64 v[222:223], s[26:27], 0, v[136:137]
	ds_read_b128 v[182:185], v152 offset:32768
	ds_read_b128 v[186:189], v152 offset:33792
	ds_read_b128 v[190:193], v152 offset:34816
	ds_read_b128 v[194:197], v152 offset:35840
	ds_read_b128 v[202:205], v152 offset:36864
	ds_read_b128 v[206:209], v152 offset:37888
	ds_read_b128 v[210:213], v152 offset:38912
	ds_read_b128 v[214:217], v152 offset:39936
	global_load_lds_dwordx4 v[222:223], off
	v_lshl_add_u64 v[222:223], s[26:27], 0, v[134:135]
	s_mov_b32 m0, s46
	s_nop 0
	global_load_lds_dwordx4 v[222:223], off
	s_waitcnt vmcnt(8)
	s_waitcnt lgkmcnt(0)
	s_barrier
	s_setprio 1
	s_waitcnt lgkmcnt(0)
	v_mfma_f32_16x16x32_bf16 v[128:131], v[142:145], v[182:185], v[128:131]
	v_mfma_f32_16x16x32_bf16 v[120:123], v[158:161], v[182:185], v[120:123]
	v_mfma_f32_16x16x32_bf16 v[112:115], v[142:145], v[190:193], v[112:115]
	v_mfma_f32_16x16x32_bf16 v[104:107], v[158:161], v[190:193], v[104:107]
	v_mfma_f32_16x16x32_bf16 v[94:97], v[142:145], v[202:205], v[94:97]
	v_mfma_f32_16x16x32_bf16 v[86:89], v[158:161], v[202:205], v[86:89]
	v_mfma_f32_16x16x32_bf16 v[78:81], v[142:145], v[210:213], v[78:81]
	v_mfma_f32_16x16x32_bf16 v[70:73], v[158:161], v[210:213], v[70:73]
	v_mfma_f32_16x16x32_bf16 v[128:131], v[154:157], v[186:189], v[128:131]
	v_mfma_f32_16x16x32_bf16 v[120:123], v[162:165], v[186:189], v[120:123]
	v_mfma_f32_16x16x32_bf16 v[112:115], v[154:157], v[194:197], v[112:115]
	v_mfma_f32_16x16x32_bf16 v[104:107], v[162:165], v[194:197], v[104:107]
	v_mfma_f32_16x16x32_bf16 v[94:97], v[154:157], v[206:209], v[94:97]
	v_mfma_f32_16x16x32_bf16 v[86:89], v[162:165], v[206:209], v[86:89]
	v_mfma_f32_16x16x32_bf16 v[78:81], v[154:157], v[214:217], v[78:81]
	v_mfma_f32_16x16x32_bf16 v[70:73], v[162:165], v[214:217], v[70:73]
	s_setprio 0
	s_setprio 1
	v_mfma_f32_16x16x32_bf16 v[124:127], v[166:169], v[182:185], v[124:127]
	v_mfma_f32_16x16x32_bf16 v[116:119], v[174:177], v[182:185], v[116:119]
	v_mfma_f32_16x16x32_bf16 v[108:111], v[166:169], v[190:193], v[108:111]
	v_mfma_f32_16x16x32_bf16 v[100:103], v[174:177], v[190:193], v[100:103]
	v_mfma_f32_16x16x32_bf16 v[90:93], v[166:169], v[202:205], v[90:93]
	v_mfma_f32_16x16x32_bf16 v[82:85], v[174:177], v[202:205], v[82:85]
	v_mfma_f32_16x16x32_bf16 v[74:77], v[166:169], v[210:213], v[74:77]
	v_mfma_f32_16x16x32_bf16 v[66:69], v[174:177], v[210:213], v[66:69]
	v_mfma_f32_16x16x32_bf16 v[124:127], v[170:173], v[186:189], v[124:127]
	v_mfma_f32_16x16x32_bf16 v[116:119], v[178:181], v[186:189], v[116:119]
	v_mfma_f32_16x16x32_bf16 v[108:111], v[170:173], v[194:197], v[108:111]
	v_mfma_f32_16x16x32_bf16 v[100:103], v[178:181], v[194:197], v[100:103]
	v_mfma_f32_16x16x32_bf16 v[90:93], v[170:173], v[206:209], v[90:93]
	v_mfma_f32_16x16x32_bf16 v[82:85], v[178:181], v[206:209], v[82:85]
	v_mfma_f32_16x16x32_bf16 v[74:77], v[170:173], v[214:217], v[74:77]
	v_mfma_f32_16x16x32_bf16 v[66:69], v[178:181], v[214:217], v[66:69]
	s_setprio 0
	s_barrier
	s_add_i32 s26, s55, s9
	v_lshl_add_u64 v[146:147], v[146:147], 0, s[28:29]
	s_mov_b32 m0, s26
	ds_read_b128 v[182:185], v152 offset:49152
	ds_read_b128 v[186:189], v152 offset:50176
	ds_read_b128 v[190:193], v152 offset:51200
	ds_read_b128 v[194:197], v152 offset:52224
	ds_read_b128 v[202:205], v152 offset:53248
	ds_read_b128 v[206:209], v152 offset:54272
	ds_read_b128 v[210:213], v152 offset:55296
	ds_read_b128 v[214:217], v152 offset:56320
	global_load_lds_dwordx4 v[146:147], off
	s_add_i32 m0, s26, 0x2000
	s_add_u32 s24, s24, 0x80080
	v_lshl_add_u64 v[146:147], v[198:199], 0, s[28:29]
	s_addc_u32 s25, s25, 0
	s_add_i32 s26, s56, s9
	global_load_lds_dwordx4 v[146:147], off
	v_lshl_add_u64 v[146:147], s[24:25], 0, v[98:99]
	s_mov_b32 m0, s26
	s_nop 0
	global_load_lds_dwordx4 v[146:147], off
	v_lshl_add_u64 v[146:147], s[24:25], 0, v[132:133]
	s_add_i32 m0, s26, 0x2000
	s_nop 0
	global_load_lds_dwordx4 v[146:147], off
	v_lshl_add_u64 v[146:147], v[218:219], 0, s[28:29]
	s_mov_b32 m0, s47
	s_nop 0
	global_load_lds_dwordx4 v[146:147], off
	v_lshl_add_u64 v[146:147], v[220:221], 0, s[28:29]
	s_mov_b32 m0, s48
	s_nop 0
	global_load_lds_dwordx4 v[146:147], off
	s_waitcnt vmcnt(8)
	s_waitcnt lgkmcnt(0)
	s_barrier
	s_setprio 1
	s_waitcnt lgkmcnt(0)
	v_mfma_f32_16x16x32_bf16 v[62:65], v[142:145], v[182:185], v[62:65]
	v_mfma_f32_16x16x32_bf16 v[54:57], v[158:161], v[182:185], v[54:57]
	v_mfma_f32_16x16x32_bf16 v[46:49], v[142:145], v[190:193], v[46:49]
	v_mfma_f32_16x16x32_bf16 v[38:41], v[158:161], v[190:193], v[38:41]
	v_mfma_f32_16x16x32_bf16 v[30:33], v[142:145], v[202:205], v[30:33]
	v_mfma_f32_16x16x32_bf16 v[22:25], v[158:161], v[202:205], v[22:25]
	v_mfma_f32_16x16x32_bf16 v[14:17], v[142:145], v[210:213], v[14:17]
	v_mfma_f32_16x16x32_bf16 v[6:9], v[158:161], v[210:213], v[6:9]
	v_mfma_f32_16x16x32_bf16 v[62:65], v[154:157], v[186:189], v[62:65]
	v_mfma_f32_16x16x32_bf16 v[54:57], v[162:165], v[186:189], v[54:57]
	v_mfma_f32_16x16x32_bf16 v[46:49], v[154:157], v[194:197], v[46:49]
	v_mfma_f32_16x16x32_bf16 v[38:41], v[162:165], v[194:197], v[38:41]
	v_mfma_f32_16x16x32_bf16 v[30:33], v[154:157], v[206:209], v[30:33]
	v_mfma_f32_16x16x32_bf16 v[22:25], v[162:165], v[206:209], v[22:25]
	v_mfma_f32_16x16x32_bf16 v[14:17], v[154:157], v[214:217], v[14:17]
	v_mfma_f32_16x16x32_bf16 v[6:9], v[162:165], v[214:217], v[6:9]
	s_setprio 0
	s_setprio 1
	v_mfma_f32_16x16x32_bf16 v[58:61], v[166:169], v[182:185], v[58:61]
	v_mfma_f32_16x16x32_bf16 v[50:53], v[174:177], v[182:185], v[50:53]
	v_mfma_f32_16x16x32_bf16 v[42:45], v[166:169], v[190:193], v[42:45]
	v_mfma_f32_16x16x32_bf16 v[34:37], v[174:177], v[190:193], v[34:37]
	v_mfma_f32_16x16x32_bf16 v[26:29], v[166:169], v[202:205], v[26:29]
	v_mfma_f32_16x16x32_bf16 v[18:21], v[174:177], v[202:205], v[18:21]
	v_mfma_f32_16x16x32_bf16 v[10:13], v[166:169], v[210:213], v[10:13]
	v_mfma_f32_16x16x32_bf16 v[2:5], v[174:177], v[210:213], v[2:5]
	v_mfma_f32_16x16x32_bf16 v[58:61], v[170:173], v[186:189], v[58:61]
	v_mfma_f32_16x16x32_bf16 v[50:53], v[178:181], v[186:189], v[50:53]
	v_mfma_f32_16x16x32_bf16 v[42:45], v[170:173], v[194:197], v[42:45]
	v_mfma_f32_16x16x32_bf16 v[34:37], v[178:181], v[194:197], v[34:37]
	v_mfma_f32_16x16x32_bf16 v[26:29], v[170:173], v[206:209], v[26:29]
	v_mfma_f32_16x16x32_bf16 v[18:21], v[178:181], v[206:209], v[18:21]
	v_mfma_f32_16x16x32_bf16 v[10:13], v[170:173], v[214:217], v[10:13]
	v_mfma_f32_16x16x32_bf16 v[2:5], v[178:181], v[214:217], v[2:5]
	s_setprio 0
	s_barrier
	s_add_i32 s54, s54, 2
	s_add_u32 s22, s22, 0x100
	s_addc_u32 s23, s23, 0
	s_add_u32 s52, s52, 0x100
	s_addc_u32 s53, s53, 0
	s_cmp_gt_u32 s54, 29
	s_cbranch_scc0 .LBB0_2461
	s_and_b64 vcc, exec, s[10:11]
	s_cbranch_vccz .LBB0_2464
	s_barrier
.LBB0_2464:
	s_and_b64 vcc, exec, s[10:11]
	s_cbranch_vccz .Lp8prio_skip
	s_setprio 2
.Lp8prio_skip:
	ds_read_b32 v154, v150
	v_mov_b32_e32 v156, v124
	v_mov_b32_e32 v157, v128
	v_mov_b32_e32 v128, v125
	v_lshl_or_b32 v144, s21, 7, v151
	s_waitcnt lgkmcnt(0)
	v_pk_mul_f32 v[156:157], v[156:157], v[154:155] op_sel_hi:[1,0]
	v_lshl_add_u32 v153, s20, 8, v148
	v_mul_f32_e32 v124, 0xbfb8aa3b, v157
	v_exp_f32_e32 v124, v124
	v_ashrrev_i32_e32 v145, 31, v144
	v_mov_b64_e32 v[142:143], s[6:7]
	s_movk_i32 s13, 0x2c00
	v_add_f32_e32 v124, 1.0, v124
	v_rcp_f32_e32 v124, v124
	v_mad_i64_i32 v[146:147], s[20:21], v153, s13, v[142:143]
	s_andn2_b64 vcc, exec, s[38:39]
	v_mul_f32_e32 v124, v157, v124
	v_mul_f32_e32 v155, v156, v124
	v_pk_mul_f32 v[124:125], v[128:129], v[154:155] op_sel_hi:[1,0]
	s_nop 0
	v_mul_f32_e32 v128, 0xbfb8aa3b, v125
	v_exp_f32_e32 v128, v128
	s_nop 0
	v_add_f32_e32 v128, 1.0, v128
	v_rcp_f32_e32 v128, v128
	s_nop 0
	v_mul_f32_e32 v125, v125, v128
	v_mul_f32_e32 v128, v124, v125
	v_mov_b32_e32 v124, v126
	v_mov_b32_e32 v125, v130
	v_pk_mul_f32 v[124:125], v[124:125], v[154:155] op_sel_hi:[1,0]
	v_mov_b32_e32 v130, v127
	v_mul_f32_e32 v126, 0xbfb8aa3b, v125
	v_exp_f32_e32 v126, v126
	s_nop 0
	v_add_f32_e32 v126, 1.0, v126
	v_rcp_f32_e32 v126, v126
	s_nop 0
	v_mul_f32_e32 v125, v125, v126
	v_mul_f32_e32 v126, v124, v125
	v_pk_mul_f32 v[124:125], v[130:131], v[154:155] op_sel_hi:[1,0]
	s_nop 0
	v_mul_f32_e32 v127, 0xbfb8aa3b, v125
	v_exp_f32_e32 v127, v127
	s_nop 0
	v_add_f32_e32 v127, 1.0, v127
	v_rcp_f32_e32 v127, v127
	s_nop 0
	v_mul_f32_e32 v125, v125, v127
	v_mul_f32_e32 v127, v124, v125
	v_mov_b32_e32 v124, v116
	v_mov_b32_e32 v125, v120
	v_pk_mul_f32 v[124:125], v[124:125], v[154:155] op_sel_hi:[1,0]
	v_mov_b32_e32 v120, v117
	v_mul_f32_e32 v116, 0xbfb8aa3b, v125
	v_exp_f32_e32 v116, v116
	s_nop 0
	v_add_f32_e32 v116, 1.0, v116
	v_rcp_f32_e32 v116, v116
	s_nop 0
	v_mul_f32_e32 v116, v125, v116
	v_mul_f32_e32 v124, v124, v116
	v_pk_mul_f32 v[116:117], v[120:121], v[154:155] op_sel_hi:[1,0]
	s_nop 0
	v_mul_f32_e32 v120, 0xbfb8aa3b, v117
	v_exp_f32_e32 v120, v120
	s_nop 0
	v_add_f32_e32 v120, 1.0, v120
	v_rcp_f32_e32 v120, v120
	s_nop 0
	v_mul_f32_e32 v117, v117, v120
	v_mul_f32_e32 v120, v116, v117
	v_mov_b32_e32 v116, v118
	v_mov_b32_e32 v117, v122
	v_pk_mul_f32 v[116:117], v[116:117], v[154:155] op_sel_hi:[1,0]
	v_mov_b32_e32 v122, v119
	v_mul_f32_e32 v118, 0xbfb8aa3b, v117
	v_exp_f32_e32 v118, v118
	s_nop 0
	v_add_f32_e32 v118, 1.0, v118
	v_rcp_f32_e32 v118, v118
	s_nop 0
	v_mul_f32_e32 v117, v117, v118
	v_mul_f32_e32 v121, v116, v117
	v_pk_mul_f32 v[116:117], v[122:123], v[154:155] op_sel_hi:[1,0]
	s_nop 0
	v_mul_f32_e32 v118, 0xbfb8aa3b, v117
	v_exp_f32_e32 v118, v118
	s_nop 0
	v_add_f32_e32 v118, 1.0, v118
	v_rcp_f32_e32 v118, v118
	s_nop 0
	v_mul_f32_e32 v117, v117, v118
	v_mul_f32_e32 v125, v116, v117
	v_lshlrev_b64 v[116:117], 1, v[144:145]
	v_lshl_add_u64 v[122:123], v[146:147], 0, v[116:117]
	v_cvt_pk_bf16_f32 v118, v155, v128
	v_cvt_pk_bf16_f32 v119, v126, v127
	v_cvt_pk_bf16_f32 v120, v124, v120
	v_cvt_pk_bf16_f32 v121, v121, v125
	global_store_dwordx4 v[122:123], v[118:121], off
	ds_read_b32 v120, v150 offset:64
	v_mov_b32_e32 v122, v108
	v_mov_b32_e32 v123, v112
	v_mov_b32_e32 v112, v109
	v_or_b32_e32 v118, 16, v153
	s_waitcnt lgkmcnt(0)
	v_pk_mul_f32 v[122:123], v[122:123], v[120:121] op_sel_hi:[1,0]
	v_mad_i64_i32 v[118:119], s[20:21], v118, s13, v[142:143]
	v_mul_f32_e32 v108, 0xbfb8aa3b, v123
	v_exp_f32_e32 v108, v108
	s_nop 0
	v_add_f32_e32 v108, 1.0, v108
	v_rcp_f32_e32 v108, v108
	s_nop 0
	v_mul_f32_e32 v108, v123, v108
	v_mul_f32_e32 v121, v122, v108
	v_pk_mul_f32 v[108:109], v[112:113], v[120:121] op_sel_hi:[1,0]
	s_nop 0
	v_mul_f32_e32 v112, 0xbfb8aa3b, v109
	v_exp_f32_e32 v112, v112
	s_nop 0
	v_add_f32_e32 v112, 1.0, v112
	v_rcp_f32_e32 v112, v112
	s_nop 0
	v_mul_f32_e32 v109, v109, v112
	v_mul_f32_e32 v112, v108, v109
	v_mov_b32_e32 v108, v110
	v_mov_b32_e32 v109, v114
	v_pk_mul_f32 v[108:109], v[108:109], v[120:121] op_sel_hi:[1,0]
	v_mov_b32_e32 v114, v111
	v_mul_f32_e32 v110, 0xbfb8aa3b, v109
	v_exp_f32_e32 v110, v110
	s_nop 0
	v_add_f32_e32 v110, 1.0, v110
	v_rcp_f32_e32 v110, v110
	s_nop 0
	v_mul_f32_e32 v109, v109, v110
	v_mul_f32_e32 v110, v108, v109
	v_pk_mul_f32 v[108:109], v[114:115], v[120:121] op_sel_hi:[1,0]
	s_nop 0
	v_mul_f32_e32 v111, 0xbfb8aa3b, v109
	v_exp_f32_e32 v111, v111
	s_nop 0
	v_add_f32_e32 v111, 1.0, v111
	v_rcp_f32_e32 v111, v111
	s_nop 0
	v_mul_f32_e32 v109, v109, v111
	v_mul_f32_e32 v111, v108, v109
	v_mov_b32_e32 v108, v100
	v_mov_b32_e32 v109, v104
	v_pk_mul_f32 v[108:109], v[108:109], v[120:121] op_sel_hi:[1,0]
	v_mov_b32_e32 v104, v101
	v_mul_f32_e32 v100, 0xbfb8aa3b, v109
	v_exp_f32_e32 v100, v100
	s_nop 0
	v_add_f32_e32 v100, 1.0, v100
	v_rcp_f32_e32 v100, v100
	s_nop 0
	v_mul_f32_e32 v100, v109, v100
	v_mul_f32_e32 v108, v108, v100
	v_pk_mul_f32 v[100:101], v[104:105], v[120:121] op_sel_hi:[1,0]
	s_nop 0
	v_mul_f32_e32 v104, 0xbfb8aa3b, v101
	v_exp_f32_e32 v104, v104
	s_nop 0
	v_add_f32_e32 v104, 1.0, v104
	v_rcp_f32_e32 v104, v104
	s_nop 0
	v_mul_f32_e32 v101, v101, v104
	v_mul_f32_e32 v109, v100, v101
	v_mov_b32_e32 v100, v102
	v_mov_b32_e32 v101, v106
	v_pk_mul_f32 v[100:101], v[100:101], v[120:121] op_sel_hi:[1,0]
	v_mov_b32_e32 v106, v103
	v_mul_f32_e32 v102, 0xbfb8aa3b, v101
	v_exp_f32_e32 v102, v102
	v_lshl_add_u64 v[104:105], v[118:119], 0, v[116:117]
	v_add_f32_e32 v102, 1.0, v102
	v_rcp_f32_e32 v102, v102
	s_nop 0
	v_mul_f32_e32 v101, v101, v102
	v_mul_f32_e32 v113, v100, v101
	v_pk_mul_f32 v[100:101], v[106:107], v[120:121] op_sel_hi:[1,0]
	s_nop 0
	v_mul_f32_e32 v102, 0xbfb8aa3b, v101
	v_exp_f32_e32 v102, v102
	s_nop 0
	v_add_f32_e32 v102, 1.0, v102
	v_rcp_f32_e32 v102, v102
	s_nop 0
	v_mul_f32_e32 v101, v101, v102
	v_mul_f32_e32 v103, v100, v101
	v_cvt_pk_bf16_f32 v100, v121, v112
	v_cvt_pk_bf16_f32 v101, v110, v111
	v_cvt_pk_bf16_f32 v102, v108, v109
	v_cvt_pk_bf16_f32 v103, v113, v103
	global_store_dwordx4 v[104:105], v[100:103], off
	ds_read_b32 v102, v150 offset:128
	v_mov_b32_e32 v104, v90
	v_mov_b32_e32 v105, v94
	v_mov_b32_e32 v94, v91
	v_or_b32_e32 v100, 32, v153
	s_waitcnt lgkmcnt(0)
	v_pk_mul_f32 v[104:105], v[104:105], v[102:103] op_sel_hi:[1,0]
	v_mad_i64_i32 v[100:101], s[20:21], v100, s13, v[142:143]
	v_mul_f32_e32 v90, 0xbfb8aa3b, v105
	v_exp_f32_e32 v90, v90
	s_nop 0
	v_add_f32_e32 v90, 1.0, v90
	v_rcp_f32_e32 v90, v90
	s_nop 0
	v_mul_f32_e32 v90, v105, v90
	v_mul_f32_e32 v103, v104, v90
	v_pk_mul_f32 v[90:91], v[94:95], v[102:103] op_sel_hi:[1,0]
	s_nop 0
	v_mul_f32_e32 v94, 0xbfb8aa3b, v91
	v_exp_f32_e32 v94, v94
	s_nop 0
	v_add_f32_e32 v94, 1.0, v94
	v_rcp_f32_e32 v94, v94
	s_nop 0
	v_mul_f32_e32 v91, v91, v94
	v_mul_f32_e32 v94, v90, v91
	v_mov_b32_e32 v90, v92
	v_mov_b32_e32 v91, v96
	v_pk_mul_f32 v[90:91], v[90:91], v[102:103] op_sel_hi:[1,0]
	v_mov_b32_e32 v96, v93
	v_mul_f32_e32 v92, 0xbfb8aa3b, v91
	v_exp_f32_e32 v92, v92
	s_nop 0
	v_add_f32_e32 v92, 1.0, v92
	v_rcp_f32_e32 v92, v92
	s_nop 0
	v_mul_f32_e32 v91, v91, v92
	v_mul_f32_e32 v92, v90, v91
	v_pk_mul_f32 v[90:91], v[96:97], v[102:103] op_sel_hi:[1,0]
	s_nop 0
	v_mul_f32_e32 v93, 0xbfb8aa3b, v91
	v_exp_f32_e32 v93, v93
	s_nop 0
	v_add_f32_e32 v93, 1.0, v93
	v_rcp_f32_e32 v93, v93
	s_nop 0
	v_mul_f32_e32 v91, v91, v93
	v_mul_f32_e32 v93, v90, v91
	v_mov_b32_e32 v90, v82
	v_mov_b32_e32 v91, v86
	v_pk_mul_f32 v[90:91], v[90:91], v[102:103] op_sel_hi:[1,0]
	v_mov_b32_e32 v86, v83
	v_mul_f32_e32 v82, 0xbfb8aa3b, v91
	v_exp_f32_e32 v82, v82
	s_nop 0
	v_add_f32_e32 v82, 1.0, v82
	v_rcp_f32_e32 v82, v82
	s_nop 0
	v_mul_f32_e32 v82, v91, v82
	v_mul_f32_e32 v90, v90, v82
	v_pk_mul_f32 v[82:83], v[86:87], v[102:103] op_sel_hi:[1,0]
	s_nop 0
	v_mul_f32_e32 v86, 0xbfb8aa3b, v83
	v_exp_f32_e32 v86, v86
	s_nop 0
	v_add_f32_e32 v86, 1.0, v86
	v_rcp_f32_e32 v86, v86
	s_nop 0
	v_mul_f32_e32 v83, v83, v86
	v_mul_f32_e32 v91, v82, v83
	v_mov_b32_e32 v82, v84
	v_mov_b32_e32 v83, v88
	v_pk_mul_f32 v[82:83], v[82:83], v[102:103] op_sel_hi:[1,0]
	v_mov_b32_e32 v88, v85
	v_mul_f32_e32 v84, 0xbfb8aa3b, v83
	v_exp_f32_e32 v84, v84
	v_lshl_add_u64 v[86:87], v[100:101], 0, v[116:117]
	v_add_f32_e32 v84, 1.0, v84
	v_rcp_f32_e32 v84, v84
	s_nop 0
	v_mul_f32_e32 v83, v83, v84
	v_mul_f32_e32 v95, v82, v83
	v_pk_mul_f32 v[82:83], v[88:89], v[102:103] op_sel_hi:[1,0]
	s_nop 0
	v_mul_f32_e32 v84, 0xbfb8aa3b, v83
	v_exp_f32_e32 v84, v84
	s_nop 0
	v_add_f32_e32 v84, 1.0, v84
	v_rcp_f32_e32 v84, v84
	s_nop 0
	v_mul_f32_e32 v83, v83, v84
	v_mul_f32_e32 v85, v82, v83
	v_cvt_pk_bf16_f32 v82, v103, v94
	v_cvt_pk_bf16_f32 v83, v92, v93
	v_cvt_pk_bf16_f32 v84, v90, v91
	v_cvt_pk_bf16_f32 v85, v95, v85
	global_store_dwordx4 v[86:87], v[82:85], off
	ds_read_b32 v84, v150 offset:192
	v_mov_b32_e32 v86, v74
	v_mov_b32_e32 v87, v78
	v_mov_b32_e32 v78, v75
	v_or_b32_e32 v82, 48, v153
	s_waitcnt lgkmcnt(0)
	v_pk_mul_f32 v[86:87], v[86:87], v[84:85] op_sel_hi:[1,0]
	v_mad_i64_i32 v[82:83], s[20:21], v82, s13, v[142:143]
	v_mul_f32_e32 v74, 0xbfb8aa3b, v87
	v_exp_f32_e32 v74, v74
	s_nop 0
	v_add_f32_e32 v74, 1.0, v74
	v_rcp_f32_e32 v74, v74
	s_nop 0
	v_mul_f32_e32 v74, v87, v74
	v_mul_f32_e32 v85, v86, v74
	v_pk_mul_f32 v[74:75], v[78:79], v[84:85] op_sel_hi:[1,0]
	s_nop 0
	v_mul_f32_e32 v78, 0xbfb8aa3b, v75
	v_exp_f32_e32 v78, v78
	s_nop 0
	v_add_f32_e32 v78, 1.0, v78
	v_rcp_f32_e32 v78, v78
	s_nop 0
	v_mul_f32_e32 v75, v75, v78
	v_mul_f32_e32 v78, v74, v75
	v_mov_b32_e32 v74, v76
	v_mov_b32_e32 v75, v80
	v_pk_mul_f32 v[74:75], v[74:75], v[84:85] op_sel_hi:[1,0]
	v_mov_b32_e32 v80, v77
	v_mul_f32_e32 v76, 0xbfb8aa3b, v75
	v_exp_f32_e32 v76, v76
	s_nop 0
	v_add_f32_e32 v76, 1.0, v76
	v_rcp_f32_e32 v76, v76
	s_nop 0
	v_mul_f32_e32 v75, v75, v76
	v_mul_f32_e32 v76, v74, v75
	v_pk_mul_f32 v[74:75], v[80:81], v[84:85] op_sel_hi:[1,0]
	s_nop 0
	v_mul_f32_e32 v77, 0xbfb8aa3b, v75
	v_exp_f32_e32 v77, v77
	s_nop 0
	v_add_f32_e32 v77, 1.0, v77
	v_rcp_f32_e32 v77, v77
	s_nop 0
	v_mul_f32_e32 v75, v75, v77
	v_mul_f32_e32 v77, v74, v75
	v_mov_b32_e32 v74, v66
	v_mov_b32_e32 v75, v70
	v_pk_mul_f32 v[74:75], v[74:75], v[84:85] op_sel_hi:[1,0]
	v_mov_b32_e32 v70, v67
	v_mul_f32_e32 v66, 0xbfb8aa3b, v75
	v_exp_f32_e32 v66, v66
	s_nop 0
	v_add_f32_e32 v66, 1.0, v66
	v_rcp_f32_e32 v66, v66
	s_nop 0
	v_mul_f32_e32 v66, v75, v66
	v_mul_f32_e32 v74, v74, v66
	v_pk_mul_f32 v[66:67], v[70:71], v[84:85] op_sel_hi:[1,0]
	s_nop 0
	v_mul_f32_e32 v70, 0xbfb8aa3b, v67
	v_exp_f32_e32 v70, v70
	s_nop 0
	v_add_f32_e32 v70, 1.0, v70
	v_rcp_f32_e32 v70, v70
	s_nop 0
	v_mul_f32_e32 v67, v67, v70
	v_mul_f32_e32 v75, v66, v67
	v_mov_b32_e32 v66, v68
	v_mov_b32_e32 v67, v72
	v_pk_mul_f32 v[66:67], v[66:67], v[84:85] op_sel_hi:[1,0]
	v_mov_b32_e32 v72, v69
	v_mul_f32_e32 v68, 0xbfb8aa3b, v67
	v_exp_f32_e32 v68, v68
	v_lshl_add_u64 v[70:71], v[82:83], 0, v[116:117]
	v_add_f32_e32 v68, 1.0, v68
	v_rcp_f32_e32 v68, v68
	s_nop 0
	v_mul_f32_e32 v67, v67, v68
	v_mul_f32_e32 v79, v66, v67
	v_pk_mul_f32 v[66:67], v[72:73], v[84:85] op_sel_hi:[1,0]
	s_nop 0
	v_mul_f32_e32 v68, 0xbfb8aa3b, v67
	v_exp_f32_e32 v68, v68
	s_nop 0
	v_add_f32_e32 v68, 1.0, v68
	v_rcp_f32_e32 v68, v68
	s_nop 0
	v_mul_f32_e32 v67, v67, v68
	v_mul_f32_e32 v69, v66, v67
	v_cvt_pk_bf16_f32 v66, v85, v78
	v_cvt_pk_bf16_f32 v67, v76, v77
	v_cvt_pk_bf16_f32 v68, v74, v75
	v_cvt_pk_bf16_f32 v69, v79, v69
	global_store_dwordx4 v[70:71], v[66:69], off
	ds_read_b32 v68, v150 offset:512
	v_mov_b32_e32 v70, v58
	v_mov_b32_e32 v71, v62
	v_mov_b32_e32 v62, v59
	v_add_u32_e32 v66, 0x80, v153
	s_waitcnt lgkmcnt(0)
	v_pk_mul_f32 v[70:71], v[70:71], v[68:69] op_sel_hi:[1,0]
	v_mad_i64_i32 v[66:67], s[20:21], v66, s13, v[142:143]
	v_mul_f32_e32 v58, 0xbfb8aa3b, v71
	v_exp_f32_e32 v58, v58
	s_nop 0
	v_add_f32_e32 v58, 1.0, v58
	v_rcp_f32_e32 v58, v58
	s_nop 0
	v_mul_f32_e32 v58, v71, v58
	v_mul_f32_e32 v69, v70, v58
	v_pk_mul_f32 v[58:59], v[62:63], v[68:69] op_sel_hi:[1,0]
	s_nop 0
	v_mul_f32_e32 v62, 0xbfb8aa3b, v59
	v_exp_f32_e32 v62, v62
	s_nop 0
	v_add_f32_e32 v62, 1.0, v62
	v_rcp_f32_e32 v62, v62
	s_nop 0
	v_mul_f32_e32 v59, v59, v62
	v_mul_f32_e32 v62, v58, v59
	v_mov_b32_e32 v58, v60
	v_mov_b32_e32 v59, v64
	v_pk_mul_f32 v[58:59], v[58:59], v[68:69] op_sel_hi:[1,0]
	v_mov_b32_e32 v64, v61
	v_mul_f32_e32 v60, 0xbfb8aa3b, v59
	v_exp_f32_e32 v60, v60
	s_nop 0
	v_add_f32_e32 v60, 1.0, v60
	v_rcp_f32_e32 v60, v60
	s_nop 0
	v_mul_f32_e32 v59, v59, v60
	v_mul_f32_e32 v60, v58, v59
	v_pk_mul_f32 v[58:59], v[64:65], v[68:69] op_sel_hi:[1,0]
	s_nop 0
	v_mul_f32_e32 v61, 0xbfb8aa3b, v59
	v_exp_f32_e32 v61, v61
	s_nop 0
	v_add_f32_e32 v61, 1.0, v61
	v_rcp_f32_e32 v61, v61
	s_nop 0
	v_mul_f32_e32 v59, v59, v61
	v_mul_f32_e32 v61, v58, v59
	v_mov_b32_e32 v58, v50
	v_mov_b32_e32 v59, v54
	v_pk_mul_f32 v[58:59], v[58:59], v[68:69] op_sel_hi:[1,0]
	v_mov_b32_e32 v54, v51
	v_mul_f32_e32 v50, 0xbfb8aa3b, v59
	v_exp_f32_e32 v50, v50
	s_nop 0
	v_add_f32_e32 v50, 1.0, v50
	v_rcp_f32_e32 v50, v50
	s_nop 0
	v_mul_f32_e32 v50, v59, v50
	v_mul_f32_e32 v58, v58, v50
	v_pk_mul_f32 v[50:51], v[54:55], v[68:69] op_sel_hi:[1,0]
	s_nop 0
	v_mul_f32_e32 v54, 0xbfb8aa3b, v51
	v_exp_f32_e32 v54, v54
	s_nop 0
	v_add_f32_e32 v54, 1.0, v54
	v_rcp_f32_e32 v54, v54
	s_nop 0
	v_mul_f32_e32 v51, v51, v54
	v_mul_f32_e32 v59, v50, v51
	v_mov_b32_e32 v50, v52
	v_mov_b32_e32 v51, v56
	v_pk_mul_f32 v[50:51], v[50:51], v[68:69] op_sel_hi:[1,0]
	v_mov_b32_e32 v56, v53
	v_mul_f32_e32 v52, 0xbfb8aa3b, v51
	v_exp_f32_e32 v52, v52
	v_lshl_add_u64 v[54:55], v[66:67], 0, v[116:117]
	v_add_f32_e32 v52, 1.0, v52
	v_rcp_f32_e32 v52, v52
	s_nop 0
	v_mul_f32_e32 v51, v51, v52
	v_mul_f32_e32 v63, v50, v51
	v_pk_mul_f32 v[50:51], v[56:57], v[68:69] op_sel_hi:[1,0]
	s_nop 0
	v_mul_f32_e32 v52, 0xbfb8aa3b, v51
	v_exp_f32_e32 v52, v52
	s_nop 0
	v_add_f32_e32 v52, 1.0, v52
	v_rcp_f32_e32 v52, v52
	s_nop 0
	v_mul_f32_e32 v51, v51, v52
	v_mul_f32_e32 v53, v50, v51
	v_cvt_pk_bf16_f32 v50, v69, v62
	v_cvt_pk_bf16_f32 v51, v60, v61
	v_cvt_pk_bf16_f32 v52, v58, v59
	v_cvt_pk_bf16_f32 v53, v63, v53
	global_store_dwordx4 v[54:55], v[50:53], off
	ds_read_b32 v52, v150 offset:576
	v_mov_b32_e32 v54, v42
	v_mov_b32_e32 v55, v46
	v_mov_b32_e32 v46, v43
	v_add_u32_e32 v50, 0x90, v153
	s_waitcnt lgkmcnt(0)
	v_pk_mul_f32 v[54:55], v[54:55], v[52:53] op_sel_hi:[1,0]
	v_mad_i64_i32 v[50:51], s[20:21], v50, s13, v[142:143]
	v_mul_f32_e32 v42, 0xbfb8aa3b, v55
	v_exp_f32_e32 v42, v42
	s_nop 0
	v_add_f32_e32 v42, 1.0, v42
	v_rcp_f32_e32 v42, v42
	s_nop 0
	v_mul_f32_e32 v42, v55, v42
	v_mul_f32_e32 v53, v54, v42
	v_pk_mul_f32 v[42:43], v[46:47], v[52:53] op_sel_hi:[1,0]
	s_nop 0
	v_mul_f32_e32 v46, 0xbfb8aa3b, v43
	v_exp_f32_e32 v46, v46
	s_nop 0
	v_add_f32_e32 v46, 1.0, v46
	v_rcp_f32_e32 v46, v46
	s_nop 0
	v_mul_f32_e32 v43, v43, v46
	v_mul_f32_e32 v46, v42, v43
	v_mov_b32_e32 v42, v44
	v_mov_b32_e32 v43, v48
	v_pk_mul_f32 v[42:43], v[42:43], v[52:53] op_sel_hi:[1,0]
	v_mov_b32_e32 v48, v45
	v_mul_f32_e32 v44, 0xbfb8aa3b, v43
	v_exp_f32_e32 v44, v44
	s_nop 0
	v_add_f32_e32 v44, 1.0, v44
	v_rcp_f32_e32 v44, v44
	s_nop 0
	v_mul_f32_e32 v43, v43, v44
	v_mul_f32_e32 v44, v42, v43
	v_pk_mul_f32 v[42:43], v[48:49], v[52:53] op_sel_hi:[1,0]
	s_nop 0
	v_mul_f32_e32 v45, 0xbfb8aa3b, v43
	v_exp_f32_e32 v45, v45
	s_nop 0
	v_add_f32_e32 v45, 1.0, v45
	v_rcp_f32_e32 v45, v45
	s_nop 0
	v_mul_f32_e32 v43, v43, v45
	v_mul_f32_e32 v45, v42, v43
	v_mov_b32_e32 v42, v34
	v_mov_b32_e32 v43, v38
	v_pk_mul_f32 v[42:43], v[42:43], v[52:53] op_sel_hi:[1,0]
	v_mov_b32_e32 v38, v35
	v_mul_f32_e32 v34, 0xbfb8aa3b, v43
	v_exp_f32_e32 v34, v34
	s_nop 0
	v_add_f32_e32 v34, 1.0, v34
	v_rcp_f32_e32 v34, v34
	s_nop 0
	v_mul_f32_e32 v34, v43, v34
	v_mul_f32_e32 v42, v42, v34
	v_pk_mul_f32 v[34:35], v[38:39], v[52:53] op_sel_hi:[1,0]
	s_nop 0
	v_mul_f32_e32 v38, 0xbfb8aa3b, v35
	v_exp_f32_e32 v38, v38
	s_nop 0
	v_add_f32_e32 v38, 1.0, v38
	v_rcp_f32_e32 v38, v38
	s_nop 0
	v_mul_f32_e32 v35, v35, v38
	v_mul_f32_e32 v43, v34, v35
	v_mov_b32_e32 v34, v36
	v_mov_b32_e32 v35, v40
	v_pk_mul_f32 v[34:35], v[34:35], v[52:53] op_sel_hi:[1,0]
	v_mov_b32_e32 v40, v37
	v_mul_f32_e32 v36, 0xbfb8aa3b, v35
	v_exp_f32_e32 v36, v36
	v_lshl_add_u64 v[38:39], v[50:51], 0, v[116:117]
	v_add_f32_e32 v36, 1.0, v36
	v_rcp_f32_e32 v36, v36
	s_nop 0
	v_mul_f32_e32 v35, v35, v36
	v_mul_f32_e32 v47, v34, v35
	v_pk_mul_f32 v[34:35], v[40:41], v[52:53] op_sel_hi:[1,0]
	s_nop 0
	v_mul_f32_e32 v36, 0xbfb8aa3b, v35
	v_exp_f32_e32 v36, v36
	s_nop 0
	v_add_f32_e32 v36, 1.0, v36
	v_rcp_f32_e32 v36, v36
	s_nop 0
	v_mul_f32_e32 v35, v35, v36
	v_mul_f32_e32 v37, v34, v35
	v_cvt_pk_bf16_f32 v34, v53, v46
	v_cvt_pk_bf16_f32 v35, v44, v45
	v_cvt_pk_bf16_f32 v36, v42, v43
	v_cvt_pk_bf16_f32 v37, v47, v37
	global_store_dwordx4 v[38:39], v[34:37], off
	ds_read_b32 v36, v150 offset:640
	v_mov_b32_e32 v38, v26
	v_mov_b32_e32 v39, v30
	v_mov_b32_e32 v30, v27
	v_add_u32_e32 v34, 0xa0, v153
	s_waitcnt lgkmcnt(0)
	v_pk_mul_f32 v[38:39], v[38:39], v[36:37] op_sel_hi:[1,0]
	v_mad_i64_i32 v[34:35], s[20:21], v34, s13, v[142:143]
	v_mul_f32_e32 v26, 0xbfb8aa3b, v39
	v_exp_f32_e32 v26, v26
	s_nop 0
	v_add_f32_e32 v26, 1.0, v26
	v_rcp_f32_e32 v26, v26
	s_nop 0
	v_mul_f32_e32 v26, v39, v26
	v_mul_f32_e32 v37, v38, v26
	v_pk_mul_f32 v[26:27], v[30:31], v[36:37] op_sel_hi:[1,0]
	s_nop 0
	v_mul_f32_e32 v30, 0xbfb8aa3b, v27
	v_exp_f32_e32 v30, v30
	s_nop 0
	v_add_f32_e32 v30, 1.0, v30
	v_rcp_f32_e32 v30, v30
	s_nop 0
	v_mul_f32_e32 v27, v27, v30
	v_mul_f32_e32 v30, v26, v27
	v_mov_b32_e32 v26, v28
	v_mov_b32_e32 v27, v32
	v_pk_mul_f32 v[26:27], v[26:27], v[36:37] op_sel_hi:[1,0]
	v_mov_b32_e32 v32, v29
	v_mul_f32_e32 v28, 0xbfb8aa3b, v27
	v_exp_f32_e32 v28, v28
	s_nop 0
	v_add_f32_e32 v28, 1.0, v28
	v_rcp_f32_e32 v28, v28
	s_nop 0
	v_mul_f32_e32 v27, v27, v28
	v_mul_f32_e32 v28, v26, v27
	v_pk_mul_f32 v[26:27], v[32:33], v[36:37] op_sel_hi:[1,0]
	s_nop 0
	v_mul_f32_e32 v29, 0xbfb8aa3b, v27
	v_exp_f32_e32 v29, v29
	s_nop 0
	v_add_f32_e32 v29, 1.0, v29
	v_rcp_f32_e32 v29, v29
	s_nop 0
	v_mul_f32_e32 v27, v27, v29
	v_mul_f32_e32 v29, v26, v27
	v_mov_b32_e32 v26, v18
	v_mov_b32_e32 v27, v22
	v_pk_mul_f32 v[26:27], v[26:27], v[36:37] op_sel_hi:[1,0]
	v_mov_b32_e32 v22, v19
	v_mul_f32_e32 v18, 0xbfb8aa3b, v27
	v_exp_f32_e32 v18, v18
	s_nop 0
	v_add_f32_e32 v18, 1.0, v18
	v_rcp_f32_e32 v18, v18
	s_nop 0
	v_mul_f32_e32 v18, v27, v18
	v_mul_f32_e32 v26, v26, v18
	v_pk_mul_f32 v[18:19], v[22:23], v[36:37] op_sel_hi:[1,0]
	s_nop 0
	v_mul_f32_e32 v22, 0xbfb8aa3b, v19
	v_exp_f32_e32 v22, v22
	s_nop 0
	v_add_f32_e32 v22, 1.0, v22
	v_rcp_f32_e32 v22, v22
	s_nop 0
	v_mul_f32_e32 v19, v19, v22
	v_mul_f32_e32 v27, v18, v19
	v_mov_b32_e32 v18, v20
	v_mov_b32_e32 v19, v24
	v_pk_mul_f32 v[18:19], v[18:19], v[36:37] op_sel_hi:[1,0]
	v_mov_b32_e32 v24, v21
	v_mul_f32_e32 v20, 0xbfb8aa3b, v19
	v_exp_f32_e32 v20, v20
	v_lshl_add_u64 v[22:23], v[34:35], 0, v[116:117]
	v_add_f32_e32 v20, 1.0, v20
	v_rcp_f32_e32 v20, v20
	s_nop 0
	v_mul_f32_e32 v19, v19, v20
	v_mul_f32_e32 v31, v18, v19
	v_pk_mul_f32 v[18:19], v[24:25], v[36:37] op_sel_hi:[1,0]
	s_nop 0
	v_mul_f32_e32 v20, 0xbfb8aa3b, v19
	v_exp_f32_e32 v20, v20
	s_nop 0
	v_add_f32_e32 v20, 1.0, v20
	v_rcp_f32_e32 v20, v20
	s_nop 0
	v_mul_f32_e32 v19, v19, v20
	v_mul_f32_e32 v21, v18, v19
	v_cvt_pk_bf16_f32 v18, v37, v30
	v_cvt_pk_bf16_f32 v19, v28, v29
	v_cvt_pk_bf16_f32 v20, v26, v27
	v_cvt_pk_bf16_f32 v21, v31, v21
	global_store_dwordx4 v[22:23], v[18:21], off
	ds_read_b32 v20, v150 offset:704
	v_mov_b32_e32 v22, v10
	v_mov_b32_e32 v23, v14
	v_mov_b32_e32 v14, v11
	v_add_u32_e32 v18, 0xb0, v153
	s_waitcnt lgkmcnt(0)
	v_pk_mul_f32 v[22:23], v[22:23], v[20:21] op_sel_hi:[1,0]
	v_mad_i64_i32 v[18:19], s[20:21], v18, s13, v[142:143]
	v_mul_f32_e32 v10, 0xbfb8aa3b, v23
	v_exp_f32_e32 v10, v10
	s_mov_b64 s[20:21], -1
	v_add_f32_e32 v10, 1.0, v10
	v_rcp_f32_e32 v10, v10
	s_nop 0
	v_mul_f32_e32 v10, v23, v10
	v_mul_f32_e32 v21, v22, v10
	v_pk_mul_f32 v[10:11], v[14:15], v[20:21] op_sel_hi:[1,0]
	s_nop 0
	v_mul_f32_e32 v14, 0xbfb8aa3b, v11
	v_exp_f32_e32 v14, v14
	s_nop 0
	v_add_f32_e32 v14, 1.0, v14
	v_rcp_f32_e32 v14, v14
	s_nop 0
	v_mul_f32_e32 v11, v11, v14
	v_mul_f32_e32 v14, v10, v11
	v_mov_b32_e32 v10, v12
	v_mov_b32_e32 v11, v16
	v_pk_mul_f32 v[10:11], v[10:11], v[20:21] op_sel_hi:[1,0]
	v_mov_b32_e32 v16, v13
	v_mul_f32_e32 v12, 0xbfb8aa3b, v11
	v_exp_f32_e32 v12, v12
	s_nop 0
	v_add_f32_e32 v12, 1.0, v12
	v_rcp_f32_e32 v12, v12
	s_nop 0
	v_mul_f32_e32 v11, v11, v12
	v_mul_f32_e32 v12, v10, v11
	v_pk_mul_f32 v[10:11], v[16:17], v[20:21] op_sel_hi:[1,0]
	s_nop 0
	v_mul_f32_e32 v13, 0xbfb8aa3b, v11
	v_exp_f32_e32 v13, v13
	s_nop 0
	v_add_f32_e32 v13, 1.0, v13
	v_rcp_f32_e32 v13, v13
	s_nop 0
	v_mul_f32_e32 v11, v11, v13
	v_mul_f32_e32 v13, v10, v11
	v_mov_b32_e32 v10, v2
	v_mov_b32_e32 v11, v6
	v_pk_mul_f32 v[10:11], v[10:11], v[20:21] op_sel_hi:[1,0]
	v_mov_b32_e32 v6, v3
	v_mul_f32_e32 v2, 0xbfb8aa3b, v11
	v_exp_f32_e32 v2, v2
	s_nop 0
	v_add_f32_e32 v2, 1.0, v2
	v_rcp_f32_e32 v2, v2
	s_nop 0
	v_mul_f32_e32 v2, v11, v2
	v_mul_f32_e32 v10, v10, v2
	v_pk_mul_f32 v[2:3], v[6:7], v[20:21] op_sel_hi:[1,0]
	s_nop 0
	v_mul_f32_e32 v6, 0xbfb8aa3b, v3
	v_exp_f32_e32 v6, v6
	s_nop 0
	v_add_f32_e32 v6, 1.0, v6
	v_rcp_f32_e32 v6, v6
	s_nop 0
	v_mul_f32_e32 v3, v3, v6
	v_mul_f32_e32 v11, v2, v3
	v_mov_b32_e32 v2, v4
	v_mov_b32_e32 v3, v8
	v_pk_mul_f32 v[2:3], v[2:3], v[20:21] op_sel_hi:[1,0]
	v_mov_b32_e32 v8, v5
	v_mul_f32_e32 v4, 0xbfb8aa3b, v3
	v_exp_f32_e32 v4, v4
	v_lshl_add_u64 v[6:7], v[18:19], 0, v[116:117]
	v_add_f32_e32 v4, 1.0, v4
	v_rcp_f32_e32 v4, v4
	s_nop 0
	v_mul_f32_e32 v3, v3, v4
	v_mul_f32_e32 v15, v2, v3
	v_pk_mul_f32 v[2:3], v[8:9], v[20:21] op_sel_hi:[1,0]
	s_nop 0
	v_mul_f32_e32 v4, 0xbfb8aa3b, v3
	v_exp_f32_e32 v4, v4
	s_nop 0
	v_add_f32_e32 v4, 1.0, v4
	v_rcp_f32_e32 v4, v4
	s_nop 0
	v_mul_f32_e32 v3, v3, v4
	v_mul_f32_e32 v5, v2, v3
	v_cvt_pk_bf16_f32 v2, v21, v14
	v_cvt_pk_bf16_f32 v3, v12, v13
	v_cvt_pk_bf16_f32 v4, v10, v11
	v_cvt_pk_bf16_f32 v5, v15, v5
	global_store_dwordx4 v[6:7], v[2:5], off
	s_setprio 0
	s_cbranch_vccnz .LBB0_2457
	s_andn2_b64 vcc, exec, s[4:5]
	s_cbranch_vccnz .LBB0_2456
	s_barrier
	s_branch .LBB0_2456
